# attention O stores paired into 16-byte stores via v_permlane16_swap + previous edits
# speedup vs baseline: 1.0085x; 1.0058x over previous
; #define LAS __attribute__((address_space(3)))
; __device__ __forceinline__ void attn_item(const Params& P, int half, int item, LAS unsigned char* lds, unsigned* ctr) {
;     ...
;     const int m0 = (16 * w < 96) ? 16 * w : 96;
;     f32x4 S[10];
; #pragma unroll
;     for (int jt = 0; jt < 10; ++jt) {
;         S[jt] = (f32x4){0.f, 0.f, 0.f, 0.f};
;         const LAS unsigned char* kr = Ks + (m0 + jt * 16 + c) * KSTR + 16 * g;
; #pragma unroll
;         for (int ks = 0; ks < 4; ++ks) { const bf16x8 a = *(const LAS bf16x8*)(kr + ks * 64); S[jt] = __builtin_amdgcn_mfma_f32_16x16x32_bf16(a, Qf[ks], S[jt], 0, 0, 0); }
;     }
.LBB0_539:
	s_or_b64 exec, exec, s[30:31]
	s_and_b32 s6, s6, -16
	v_and_b32_e32 v54, 15, v137
	s_min_i32 s6, s6, 0x60
	v_or_b32_e32 v18, s6, v54
	s_movk_i32 s7, 0x110
	v_mul_lo_u32 v18, v18, s7
	v_add3_u32 v55, 0, v194, v18
	ds_read_b128 v[204:207], v55
	ds_read_b128 v[208:211], v55 offset:64
	ds_read_b128 v[212:215], v55 offset:4416
	ds_read_b128 v[216:219], v55 offset:8768
	ds_read_b128 v[220:223], v55 offset:13120
	ds_read_b128 v[224:227], v55 offset:128
	s_and_b32 s5, s5, 0xff
	s_cmp_eq_u32 s5, 0
	s_cselect_b64 vcc, -1, 0
	s_mov_b32 s5, 0xff800000
	v_lshlrev_b32_e32 v194, 3, v136
	s_waitcnt lgkmcnt(5)
	v_mfma_f32_16x16x32_bf16 v[18:21], v[204:207], v[6:9], 0
	ds_read_b128 v[204:207], v55 offset:17472
	ds_read_b128 v[236:239], v55 offset:21824
	ds_read_b128 v[240:243], v55 offset:192
	s_waitcnt lgkmcnt(7)
	v_mfma_f32_16x16x32_bf16 v[18:21], v[208:211], v[14:17], v[18:21]
	ds_read_b128 v[208:211], v55 offset:26176
	ds_read_b128 v[244:247], v55 offset:30528
	ds_read_b128 v[176:179], v55 offset:4352
	s_waitcnt lgkmcnt(6)
	v_mfma_f32_16x16x32_bf16 v[18:21], v[224:227], v[2:5], v[18:21]
	ds_read_b128 v[224:227], v55 offset:34880
	ds_read_b128 v[180:183], v55 offset:4480
	ds_read_b128 v[184:187], v55 offset:4544
	s_waitcnt lgkmcnt(6)
	v_mfma_f32_16x16x32_bf16 v[18:21], v[240:243], v[10:13], v[18:21]
	ds_read_b128 v[240:243], v55 offset:8704
	ds_read_b128 v[188:191], v55 offset:8832
	s_waitcnt lgkmcnt(5)
	v_mfma_f32_16x16x32_bf16 v[22:25], v[176:179], v[6:9], 0
	v_mfma_f32_16x16x32_bf16 v[22:25], v[212:215], v[14:17], v[22:25]
	ds_read_b128 v[212:215], v55 offset:8896
	s_waitcnt lgkmcnt(4)
	v_mfma_f32_16x16x32_bf16 v[22:25], v[180:183], v[2:5], v[22:25]
	ds_read_b128 v[176:179], v55 offset:13056
	s_waitcnt lgkmcnt(4)
	v_mfma_f32_16x16x32_bf16 v[22:25], v[184:187], v[10:13], v[22:25]
	ds_read_b128 v[180:183], v55 offset:13184
	s_waitcnt lgkmcnt(4)
	v_mfma_f32_16x16x32_bf16 v[26:29], v[240:243], v[6:9], 0
	v_mfma_f32_16x16x32_bf16 v[26:29], v[216:219], v[14:17], v[26:29]
	ds_read_b128 v[216:219], v55 offset:13248
	s_waitcnt lgkmcnt(4)
	v_mfma_f32_16x16x32_bf16 v[26:29], v[188:191], v[2:5], v[26:29]
	ds_read_b128 v[240:243], v55 offset:17408
	s_waitcnt lgkmcnt(4)
	v_mfma_f32_16x16x32_bf16 v[26:29], v[212:215], v[10:13], v[26:29]
	ds_read_b128 v[212:215], v55 offset:17536
	s_waitcnt lgkmcnt(4)
	v_mfma_f32_16x16x32_bf16 v[30:33], v[176:179], v[6:9], 0
	v_mfma_f32_16x16x32_bf16 v[30:33], v[220:223], v[14:17], v[30:33]
	ds_read_b128 v[220:223], v55 offset:17600
	s_waitcnt lgkmcnt(4)
	v_mfma_f32_16x16x32_bf16 v[30:33], v[180:183], v[2:5], v[30:33]
	ds_read_b128 v[176:179], v55 offset:21760
	s_waitcnt lgkmcnt(4)
	v_mfma_f32_16x16x32_bf16 v[30:33], v[216:219], v[10:13], v[30:33]
	ds_read_b128 v[216:219], v55 offset:21888
	s_waitcnt lgkmcnt(4)
	v_mfma_f32_16x16x32_bf16 v[34:37], v[240:243], v[6:9], 0
	v_mfma_f32_16x16x32_bf16 v[34:37], v[204:207], v[14:17], v[34:37]
	ds_read_b128 v[204:207], v55 offset:21952
	s_waitcnt lgkmcnt(4)
	v_mfma_f32_16x16x32_bf16 v[34:37], v[212:215], v[2:5], v[34:37]
	ds_read_b128 v[212:215], v55 offset:26112
	s_waitcnt lgkmcnt(4)
	v_mfma_f32_16x16x32_bf16 v[34:37], v[220:223], v[10:13], v[34:37]
	ds_read_b128 v[220:223], v55 offset:26240
	s_waitcnt lgkmcnt(4)
	v_mfma_f32_16x16x32_bf16 v[38:41], v[176:179], v[6:9], 0
	v_mfma_f32_16x16x32_bf16 v[38:41], v[236:239], v[14:17], v[38:41]
	ds_read_b128 v[236:239], v55 offset:26304
	s_waitcnt lgkmcnt(4)
	v_mfma_f32_16x16x32_bf16 v[38:41], v[216:219], v[2:5], v[38:41]
	ds_read_b128 v[216:219], v55 offset:30464
	s_waitcnt lgkmcnt(4)
	v_mfma_f32_16x16x32_bf16 v[38:41], v[204:207], v[10:13], v[38:41]
	ds_read_b128 v[204:207], v55 offset:30592
	s_waitcnt lgkmcnt(4)
	v_mfma_f32_16x16x32_bf16 v[42:45], v[212:215], v[6:9], 0
	v_mfma_f32_16x16x32_bf16 v[42:45], v[208:211], v[14:17], v[42:45]
	ds_read_b128 v[208:211], v55 offset:30656
	s_waitcnt lgkmcnt(4)
	v_mfma_f32_16x16x32_bf16 v[42:45], v[220:223], v[2:5], v[42:45]
	ds_read_b128 v[212:215], v55 offset:34816
	s_waitcnt lgkmcnt(4)
	v_mfma_f32_16x16x32_bf16 v[42:45], v[236:239], v[10:13], v[42:45]
	ds_read_b128 v[220:223], v55 offset:34944
	s_waitcnt lgkmcnt(4)
	v_mfma_f32_16x16x32_bf16 v[46:49], v[216:219], v[6:9], 0
	v_mfma_f32_16x16x32_bf16 v[46:49], v[244:247], v[14:17], v[46:49]
	ds_read_b128 v[216:219], v55 offset:35008
	s_waitcnt lgkmcnt(4)
	v_mfma_f32_16x16x32_bf16 v[46:49], v[204:207], v[2:5], v[46:49]
	ds_read_b128 v[204:207], v55 offset:39168
	s_waitcnt lgkmcnt(4)
	v_mfma_f32_16x16x32_bf16 v[46:49], v[208:211], v[10:13], v[46:49]
	ds_read_b128 v[208:211], v55 offset:39232
	s_waitcnt lgkmcnt(4)
	v_mfma_f32_16x16x32_bf16 v[50:53], v[212:215], v[6:9], 0
	v_mfma_f32_16x16x32_bf16 v[50:53], v[224:227], v[14:17], v[50:53]
	ds_read_b128 v[212:215], v55 offset:39296
	s_waitcnt lgkmcnt(4)
	v_mfma_f32_16x16x32_bf16 v[50:53], v[220:223], v[2:5], v[50:53]
	ds_read_b128 v[220:223], v55 offset:39360
	s_waitcnt lgkmcnt(4)
	v_mfma_f32_16x16x32_bf16 v[50:53], v[216:219], v[10:13], v[50:53]
	s_nop 0
	s_waitcnt lgkmcnt(3)
	v_mfma_f32_16x16x32_bf16 v[6:9], v[204:207], v[6:9], 0
	s_nop 0
	s_waitcnt lgkmcnt(2)
	v_mfma_f32_16x16x32_bf16 v[6:9], v[208:211], v[14:17], v[6:9]
	s_nop 0
	s_waitcnt lgkmcnt(1)
	v_mfma_f32_16x16x32_bf16 v[2:5], v[212:215], v[2:5], v[6:9]
	s_nop 4
	s_nop 0
	s_waitcnt lgkmcnt(0)
; __device__ __forceinline__ void attn_item(const Params& P, int half, int item, LAS unsigned char* lds, unsigned* ctr) {
;     ...
;     float mx = -INFINITY;
;     const int dbase = qi + 128 - m0 - 4 * g;
;     const unsigned dlim = (unsigned)((n == 0) ? (qi < 128 ? qi : 128) : 128);
; #pragma unroll
;     for (int jt = 0; jt < 10; ++jt)
; #pragma unroll
;         for (int jj = 0; jj < 4; ++jj) { const bool ok = (unsigned)(dbase - (jt * 16 + jj)) <= dlim;
;             const float s = ok ? S[jt][jj] : -INFINITY; S[jt][jj] = s; mx = fmaxf(mx, s); }
;     mx = fmaxf(mx, __shfl_xor(mx, 16)); mx = fmaxf(mx, __shfl_xor(mx, 32));
	v_mfma_f32_16x16x32_bf16 v[2:5], v[220:223], v[10:13], v[2:5]
	v_lshlrev_b32_e32 v6, 2, v136
	v_min_i32_e32 v7, 0x80, v138
	v_mov_b32_e32 v8, 0x80
	v_or_b32_e32 v55, s6, v6
	v_cndmask_b32_e32 v7, v8, v7, vcc
	v_add_u32_e32 v8, 0x80, v138
	v_sub_u32_e32 v9, v8, v55
	v_bitop3_b32 v6, s6, v6, s6 bitop3:3
	v_cmp_le_u32_e32 vcc, v9, v7
	v_add_u32_e32 v8, v8, v6
	v_sub_u32_e32 v11, v138, v55
	v_cndmask_b32_e32 v9, v235, v18, vcc
	v_cmp_le_u32_e32 vcc, v8, v7
	v_add_u32_e32 v12, 0x7e, v11
	v_add_u32_e32 v13, 0x7d, v11
	v_cndmask_b32_e32 v8, v235, v19, vcc
	v_cmp_le_u32_e32 vcc, v12, v7
	v_add_u32_e32 v14, 0x70, v11
	v_add_u32_e32 v15, 0x6f, v11
	v_cndmask_b32_e32 v12, v235, v20, vcc
	v_cmp_le_u32_e32 vcc, v13, v7
	v_add_u32_e32 v16, 0x6e, v11
	v_add_u32_e32 v17, 0x6d, v11
	v_cndmask_b32_e32 v13, v235, v21, vcc
	v_cmp_le_u32_e32 vcc, v14, v7
	v_add_u32_e32 v18, 0x60, v11
	v_add_u32_e32 v19, 0x5f, v11
	v_cndmask_b32_e32 v14, v235, v22, vcc
	v_cmp_le_u32_e32 vcc, v15, v7
	v_add_u32_e32 v20, 0x5e, v11
	v_add_u32_e32 v21, 0x5d, v11
	v_cndmask_b32_e32 v15, v235, v23, vcc
	v_cmp_le_u32_e32 vcc, v16, v7
	v_add_u32_e32 v22, 0x50, v11
	v_add_u32_e32 v23, 0x4f, v11
	v_cndmask_b32_e32 v16, v235, v24, vcc
	v_cmp_le_u32_e32 vcc, v17, v7
	v_max3_f32 v10, v9, s5, v8
	v_max3_f32 v10, v10, v12, v13
	v_cndmask_b32_e32 v17, v235, v25, vcc
	v_cmp_le_u32_e32 vcc, v18, v7
	v_max3_f32 v10, v10, v14, v15
	v_max3_f32 v10, v10, v16, v17
	v_cndmask_b32_e32 v18, v235, v26, vcc
	v_cmp_le_u32_e32 vcc, v19, v7
	v_add_u32_e32 v6, v138, v6
	v_readlane_b32 s5, v255, 16
	v_cndmask_b32_e32 v19, v235, v27, vcc
	v_cmp_le_u32_e32 vcc, v20, v7
	v_max3_f32 v10, v10, v18, v19
	s_nop 0
	v_cndmask_b32_e32 v20, v235, v28, vcc
	v_cmp_le_u32_e32 vcc, v21, v7
	s_nop 1
	v_cndmask_b32_e32 v21, v235, v29, vcc
	v_cmp_le_u32_e32 vcc, v22, v7
	v_max3_f32 v10, v10, v20, v21
	s_nop 0
	v_cndmask_b32_e32 v22, v235, v30, vcc
	v_cmp_le_u32_e32 vcc, v23, v7
	v_add_u32_e32 v23, 0x4e, v11
	s_nop 0
	v_cndmask_b32_e32 v25, v235, v31, vcc
	v_cmp_le_u32_e32 vcc, v23, v7
	v_add_u32_e32 v23, 0x4d, v11
	v_max3_f32 v10, v10, v22, v25
	v_cndmask_b32_e32 v26, v235, v32, vcc
	v_cmp_le_u32_e32 vcc, v23, v7
	v_add_u32_e32 v23, 64, v11
	s_nop 0
	v_cndmask_b32_e32 v27, v235, v33, vcc
	v_cmp_le_u32_e32 vcc, v23, v7
	v_add_u32_e32 v23, 63, v11
	v_max3_f32 v10, v10, v26, v27
	v_cndmask_b32_e32 v28, v235, v34, vcc
	v_cmp_le_u32_e32 vcc, v23, v7
	v_add_u32_e32 v23, 62, v11
	s_nop 0
	v_cndmask_b32_e32 v29, v235, v35, vcc
	v_cmp_le_u32_e32 vcc, v23, v7
	v_add_u32_e32 v23, 61, v11
	v_max3_f32 v10, v10, v28, v29
	v_cndmask_b32_e32 v30, v235, v36, vcc
	v_cmp_le_u32_e32 vcc, v23, v7
	v_add_u32_e32 v23, 48, v11
	s_nop 0
	v_cndmask_b32_e32 v31, v235, v37, vcc
	v_cmp_le_u32_e32 vcc, v23, v7
	v_add_u32_e32 v23, 47, v11
	v_max3_f32 v10, v10, v30, v31
	v_cndmask_b32_e32 v34, v235, v38, vcc
	v_cmp_le_u32_e32 vcc, v23, v7
	v_add_u32_e32 v23, 46, v11
	s_nop 0
	v_cndmask_b32_e32 v35, v235, v39, vcc
	v_cmp_le_u32_e32 vcc, v23, v7
	v_add_u32_e32 v23, 45, v11
	v_max3_f32 v10, v10, v34, v35
	v_cndmask_b32_e32 v36, v235, v40, vcc
	v_cmp_le_u32_e32 vcc, v23, v7
	v_add_u32_e32 v23, 32, v11
	s_nop 0
	v_cndmask_b32_e32 v37, v235, v41, vcc
	v_cmp_le_u32_e32 vcc, v23, v7
	v_add_u32_e32 v23, 31, v11
	v_max3_f32 v10, v10, v36, v37
	v_cndmask_b32_e32 v38, v235, v42, vcc
	v_cmp_le_u32_e32 vcc, v23, v7
	v_add_u32_e32 v23, 30, v11
	s_nop 0
	v_cndmask_b32_e32 v39, v235, v43, vcc
	v_cmp_le_u32_e32 vcc, v23, v7
	v_add_u32_e32 v23, 29, v11
	v_max3_f32 v10, v10, v38, v39
	v_cndmask_b32_e32 v40, v235, v44, vcc
	v_cmp_le_u32_e32 vcc, v23, v7
	v_add_u32_e32 v23, 16, v11
	s_nop 0
	v_cndmask_b32_e32 v41, v235, v45, vcc
	v_cmp_le_u32_e32 vcc, v23, v7
	v_add_u32_e32 v23, 15, v11
	v_max3_f32 v10, v10, v40, v41
	v_cndmask_b32_e32 v42, v235, v46, vcc
	v_cmp_le_u32_e32 vcc, v23, v7
	v_add_u32_e32 v23, 14, v11
	s_nop 0
	v_cndmask_b32_e32 v43, v235, v47, vcc
	v_cmp_le_u32_e32 vcc, v23, v7
	v_add_u32_e32 v23, 13, v11
	v_max3_f32 v10, v10, v42, v43
	v_cndmask_b32_e32 v44, v235, v48, vcc
	v_cmp_le_u32_e32 vcc, v23, v7
	s_nop 1
	v_cndmask_b32_e32 v45, v235, v49, vcc
	v_cmp_le_u32_e32 vcc, v11, v7
	v_max3_f32 v10, v10, v44, v45
	s_nop 0
	v_cndmask_b32_e32 v46, v235, v50, vcc
	v_cmp_le_u32_e32 vcc, v6, v7
	s_nop 1
	v_cndmask_b32_e32 v47, v235, v51, vcc
	v_max3_f32 v6, v10, v46, v47
	v_add_u32_e32 v10, -2, v11
	v_cmp_le_u32_e32 vcc, v10, v7
	v_add_u32_e32 v10, -3, v11
	s_nop 0
	v_cndmask_b32_e32 v48, v235, v52, vcc
	v_cmp_le_u32_e32 vcc, v10, v7
	v_add_u32_e32 v10, -16, v11
	s_nop 0
	v_cndmask_b32_e32 v49, v235, v53, vcc
	v_cmp_le_u32_e32 vcc, v10, v7
	v_max3_f32 v6, v6, v48, v49
	s_nop 0
	v_cndmask_b32_e32 v50, v235, v2, vcc
	v_subrev_u32_e32 v2, 17, v11
	v_cmp_le_u32_e32 vcc, v2, v7
	s_nop 1
	v_cndmask_b32_e32 v51, v235, v3, vcc
	v_subrev_u32_e32 v3, 18, v11
	v_cmp_le_u32_e32 vcc, v3, v7
	v_subrev_u32_e32 v3, 19, v11
	v_max3_f32 v2, v6, v50, v51
	v_cndmask_b32_e32 v52, v235, v4, vcc
	v_and_b32_e32 v4, 64, v230
	v_cmp_le_u32_e32 vcc, v3, v7
	v_xor_b32_e32 v3, 16, v230
	v_add_u32_e32 v4, 64, v4
	v_cndmask_b32_e32 v53, v235, v5, vcc
	v_cmp_lt_i32_e32 vcc, v3, v4
	v_max3_f32 v2, v2, v52, v53
	s_nop 0
	v_cndmask_b32_e32 v3, v230, v3, vcc
	v_lshlrev_b32_e32 v56, 2, v3
	ds_bpermute_b32 v3, v56, v2
	s_waitcnt lgkmcnt(0)
	v_max_f32_e32 v3, v3, v3
	v_max_f32_e32 v2, v2, v3
	v_xor_b32_e32 v3, 32, v230
	v_cmp_lt_i32_e32 vcc, v3, v4
	s_nop 1
	v_cndmask_b32_e32 v3, v230, v3, vcc
	v_lshlrev_b32_e32 v57, 2, v3
	ds_bpermute_b32 v3, v57, v2
	s_waitcnt lgkmcnt(0)
; #define LAS __attribute__((address_space(3)))
; __device__ __forceinline__ unsigned cvt_pk_bf16(float lo, float hi) { unsigned r; asm volatile("v_cvt_pk_bf16_f32 %0, %1, %2" : "=v"(r) : "v"(lo), "v"(hi)); return r; }
; __device__ __forceinline__ void attn_item(const Params& P, int half, int item, LAS unsigned char* lds, unsigned* ctr) {
;     ...
;     float den = 0.f;
; #pragma unroll
;     for (int jt = 0; jt < 10; ++jt) { const f32x4 d = S[jt] - mx; f32x4 p; p[0] = __builtin_amdgcn_exp2f(d[0]); p[1] = __builtin_amdgcn_exp2f(d[1]); p[2] = __builtin_amdgcn_exp2f(d[2]); p[3] = __builtin_amdgcn_exp2f(d[3]);
;         S[jt] = p; den += (p[0] + p[1]) + (p[2] + p[3]); }
;     den += __shfl_xor(den, 16); den += __shfl_xor(den, 32);
;     bf16x8 Pf[5];
; #pragma unroll
;     for (int k5 = 0; k5 < 5; ++k5) { u32x4 pw; pw.x = cvt_pk_bf16(S[2 * k5][0], S[2 * k5][1]); pw.y = cvt_pk_bf16(S[2 * k5][2], S[2 * k5][3]); pw.z = cvt_pk_bf16(S[2 * k5 + 1][0], S[2 * k5 + 1][1]); pw.w = cvt_pk_bf16(S[2 * k5 + 1][2], S[2 * k5 + 1][3]); Pf[k5] = as_bf16x8(pw); }
;     const float inv = 1.0f / den;
;     bf16_t* op = Z + (size_t)qrow * ZC + colq + 4 * g;
; #pragma unroll
;     for (int dt = 0; dt < 8; ++dt) {
;         f32x4 O = (f32x4){0.f, 0.f, 0.f, 0.f};
;         const LAS unsigned char* vr = Vt + (dt * 16 + c) * VSTR + (m0 + 4 * g) * 2;
; #pragma unroll
;         for (int k5 = 0; k5 < 5; ++k5) { const u32x2 lo = *(const LAS u32x2*)(vr + k5 * 64), hi = *(const LAS u32x2*)(vr + k5 * 64 + 32);
;             const bf16x8 a = as_bf16x8((u32x4){lo.x, lo.y, hi.x, hi.y}); O = __builtin_amdgcn_mfma_f32_16x16x32_bf16(a, Pf[k5], O, 0, 0, 0); }
;         u32x2 ow; ow.x = cvt_pk_bf16(O[0] * inv, O[1] * inv); ow.y = cvt_pk_bf16(O[2] * inv, O[3] * inv);
;         *(u32x2*)(op + dt * 16) = ow;
	v_max_f32_e32 v3, v3, v3
	v_max_f32_e32 v24, v2, v3
	v_sub_f32_e32 v2, v13, v24
	v_sub_f32_e32 v3, v12, v24
	v_sub_f32_e32 v5, v8, v24
	v_sub_f32_e32 v4, v9, v24
	v_exp_f32_e32 v4, v4
	v_exp_f32_e32 v6, v5
	v_exp_f32_e32 v5, v3
	v_exp_f32_e32 v7, v2
	v_sub_f32_e32 v9, v16, v24
	v_sub_f32_e32 v10, v15, v24
	v_sub_f32_e32 v8, v14, v24
	v_pk_add_f32 v[2:3], v[4:5], v[6:7]
	v_exp_f32_e32 v8, v8
	v_add_f32_e32 v2, v2, v3
	v_add_f32_e32 v3, 0, v2
	v_sub_f32_e32 v2, v17, v24
	v_exp_f32_e32 v10, v10
	v_exp_f32_e32 v9, v9
	v_exp_f32_e32 v11, v2
	v_sub_f32_e32 v2, v21, v24
	v_sub_f32_e32 v14, v19, v24
	v_sub_f32_e32 v15, v18, v24
	v_pk_add_f32 v[12:13], v[8:9], v[10:11]
	v_exp_f32_e32 v58, v15
	v_pk_add_f32 v[12:13], v[12:13], v[12:13] op_sel_hi:[0,1]
	v_sub_f32_e32 v12, v20, v24
	v_exp_f32_e32 v59, v14
	v_exp_f32_e32 v60, v12
	v_exp_f32_e32 v61, v2
	v_sub_f32_e32 v2, v27, v24
	v_sub_f32_e32 v12, v26, v24
	v_sub_f32_e32 v14, v25, v24
	v_sub_f32_e32 v15, v22, v24
	v_exp_f32_e32 v16, v15
	v_exp_f32_e32 v22, v14
	v_exp_f32_e32 v12, v12
	v_exp_f32_e32 v2, v2
	v_add_f32_e32 v17, v58, v59
	v_add_f32_e32 v23, v60, v61
	v_pk_add_f32 v[14:15], v[16:17], v[22:23]
	v_pk_add_f32 v[18:19], v[12:13], v[2:3]
	v_sub_f32_e32 v3, v31, v24
	v_pk_add_f32 v[14:15], v[14:15], v[18:19]
	v_sub_f32_e32 v13, v30, v24
	v_pk_add_f32 v[26:27], v[14:15], v[14:15] op_sel_hi:[0,1]
	v_sub_f32_e32 v14, v29, v24
	v_sub_f32_e32 v15, v28, v24
	v_exp_f32_e32 v28, v15
	v_exp_f32_e32 v30, v14
	v_exp_f32_e32 v29, v13
	v_exp_f32_e32 v31, v3
	v_sub_f32_e32 v3, v37, v24
	v_sub_f32_e32 v13, v36, v24
	v_exp_f32_e32 v13, v13
	v_pk_add_f32 v[14:15], v[28:29], v[30:31]
	v_exp_f32_e32 v3, v3
	v_pk_add_f32 v[32:33], v[14:15], v[14:15] op_sel_hi:[0,1]
	v_sub_f32_e32 v14, v35, v24
	v_sub_f32_e32 v15, v34, v24
	v_exp_f32_e32 v23, v15
	v_exp_f32_e32 v25, v14
	v_sub_f32_e32 v14, v41, v24
	v_sub_f32_e32 v15, v40, v24
	v_sub_f32_e32 v17, v39, v24
	v_sub_f32_e32 v18, v38, v24
	v_exp_f32_e32 v34, v18
	v_exp_f32_e32 v36, v17
	v_exp_f32_e32 v32, v15
	v_exp_f32_e32 v26, v14
	v_add_f32_e32 v35, v23, v25
	v_add_f32_e32 v37, v13, v3
	v_pk_add_f32 v[14:15], v[34:35], v[36:37]
	v_pk_add_f32 v[18:19], v[32:33], v[26:27]
	v_sub_f32_e32 v17, v43, v24
	v_pk_add_f32 v[14:15], v[14:15], v[18:19]
	v_sub_f32_e32 v18, v42, v24
	v_pk_add_f32 v[38:39], v[14:15], v[14:15] op_sel_hi:[0,1]
	v_sub_f32_e32 v14, v45, v24
	v_sub_f32_e32 v15, v44, v24
	v_exp_f32_e32 v40, v18
	v_exp_f32_e32 v42, v17
	v_exp_f32_e32 v41, v15
	v_exp_f32_e32 v43, v14
	v_sub_f32_e32 v17, v47, v24
	v_sub_f32_e32 v18, v46, v24
	v_exp_f32_e32 v27, v18
	v_pk_add_f32 v[14:15], v[40:41], v[42:43]
	v_exp_f32_e32 v33, v17
	v_pk_add_f32 v[44:45], v[14:15], v[14:15] op_sel_hi:[0,1]
	v_sub_f32_e32 v14, v49, v24
	v_sub_f32_e32 v15, v48, v24
	v_exp_f32_e32 v35, v15
	v_exp_f32_e32 v37, v14
	v_sub_f32_e32 v14, v53, v24
	v_sub_f32_e32 v15, v52, v24
	v_sub_f32_e32 v17, v51, v24
	v_sub_f32_e32 v18, v50, v24
	v_exp_f32_e32 v46, v18
	v_exp_f32_e32 v48, v17
	v_exp_f32_e32 v44, v15
	v_exp_f32_e32 v38, v14
	v_add_f32_e32 v47, v27, v33
	v_add_f32_e32 v49, v35, v37
	v_pk_add_f32 v[14:15], v[46:47], v[48:49]
	v_pk_add_f32 v[18:19], v[44:45], v[38:39]
	s_nop 0
	v_pk_add_f32 v[14:15], v[14:15], v[18:19]
	v_cvt_pk_bf16_f32 v18, v4, v6
	v_cvt_pk_bf16_f32 v19, v5, v7
	v_cvt_pk_bf16_f32 v20, v8, v10
	v_cvt_pk_bf16_f32 v21, v9, v11
	s_nop 0
	v_add_f32_e32 v14, v14, v15
	ds_bpermute_b32 v15, v56, v14
	s_waitcnt lgkmcnt(0)
	v_add_f32_e32 v39, v14, v15
	ds_bpermute_b32 v45, v57, v39
	v_cvt_pk_bf16_f32 v14, v58, v59
	v_cvt_pk_bf16_f32 v15, v60, v61
	v_cvt_pk_bf16_f32 v16, v16, v22
	v_cvt_pk_bf16_f32 v17, v12, v2
	v_cvt_pk_bf16_f32 v10, v28, v30
	v_cvt_pk_bf16_f32 v11, v29, v31
	v_cvt_pk_bf16_f32 v12, v23, v25
	s_waitcnt lgkmcnt(0)
	v_add_f32_e32 v25, v39, v45
	v_div_scale_f32 v22, s[6:7], v25, v25, 1.0
	v_rcp_f32_e32 v23, v22
	v_cvt_pk_bf16_f32 v13, v13, v3
	v_cvt_pk_bf16_f32 v6, v34, v36
	v_cvt_pk_bf16_f32 v7, v32, v26
	v_cvt_pk_bf16_f32 v8, v40, v42
	v_cvt_pk_bf16_f32 v9, v41, v43
	s_nop 0
	v_fma_f32 v26, -v22, v23, 1.0
	v_fmac_f32_e32 v23, v26, v23
	v_div_scale_f32 v26, vcc, 1.0, v25, 1.0
	v_cvt_pk_bf16_f32 v2, v27, v33
	v_mul_f32_e32 v27, v26, v23
	v_fma_f32 v28, -v22, v27, v26
	v_fmac_f32_e32 v27, v28, v23
	v_fma_f32 v22, -v22, v27, v26
	v_div_fmas_f32 v22, v22, v23, v27
	v_lshlrev_b32_e32 v27, 1, v55
	v_mul_u32_u24_e32 v28, 0x210, v54
	v_add3_u32 v27, s5, v27, v28
	v_cvt_pk_bf16_f32 v3, v35, v37
	v_cvt_pk_bf16_f32 v4, v46, v48
	v_cvt_pk_bf16_f32 v5, v44, v38
	ds_read2_b64 v[204:207], v27 offset1:4
	ds_read2_b64 v[208:211], v27 offset0:8 offset1:12
	ds_read2_b64 v[212:215], v27 offset0:16 offset1:20
	ds_read2_b64 v[216:219], v27 offset0:24 offset1:28
	ds_read2_b64 v[220:223], v27 offset0:32 offset1:36
	s_nop 0
	s_waitcnt lgkmcnt(4)
	v_mfma_f32_16x16x32_bf16 v[28:31], v[204:207], v[18:21], 0
	v_div_fixup_f32 v26, v22, v25, 1.0
	v_lshl_add_u64 v[22:23], v[130:131], 0, v[194:195]
	v_and_b32_e32 v192, 16, v230
	v_lshrrev_b32_e32 v193, 1, v192
	v_add_u32_e32 v192, v192, v193
	v_mov_b32_e32 v193, 0
	v_lshl_add_u64 v[192:193], v[22:23], 0, v[192:193]
	v_add_u32_e32 v36, 0x2000, v27
	s_waitcnt lgkmcnt(3)
	v_mfma_f32_16x16x32_bf16 v[28:31], v[208:211], v[14:17], v[28:31]
	s_nop 0
	v_cmp_eq_u32_e32 vcc, 0, v136
	s_waitcnt lgkmcnt(2)
	v_mfma_f32_16x16x32_bf16 v[28:31], v[212:215], v[10:13], v[28:31]
	s_nop 0
	s_waitcnt lgkmcnt(1)
	v_mfma_f32_16x16x32_bf16 v[28:31], v[216:219], v[6:9], v[28:31]
	s_nop 0
	s_waitcnt lgkmcnt(0)
; #define LAS __attribute__((address_space(3)))
; __device__ __forceinline__ unsigned cvt_pk_bf16(float lo, float hi) { unsigned r; asm volatile("v_cvt_pk_bf16_f32 %0, %1, %2" : "=v"(r) : "v"(lo), "v"(hi)); return r; }
; __device__ __forceinline__ void attn_item(const Params& P, int half, int item, LAS unsigned char* lds, unsigned* ctr) {
;     ...
;     for (int dt = 0; dt < 8; ++dt) {
;         f32x4 O = (f32x4){0.f, 0.f, 0.f, 0.f};
;         const LAS unsigned char* vr = Vt + (dt * 16 + c) * VSTR + (m0 + 4 * g) * 2;
; #pragma unroll
;         for (int k5 = 0; k5 < 5; ++k5) { const u32x2 lo = *(const LAS u32x2*)(vr + k5 * 64), hi = *(const LAS u32x2*)(vr + k5 * 64 + 32);
;             const bf16x8 a = as_bf16x8((u32x4){lo.x, lo.y, hi.x, hi.y}); O = __builtin_amdgcn_mfma_f32_16x16x32_bf16(a, Pf[k5], O, 0, 0, 0); }
;         u32x2 ow; ow.x = cvt_pk_bf16(O[0] * inv, O[1] * inv); ow.y = cvt_pk_bf16(O[2] * inv, O[3] * inv);
;         *(u32x2*)(op + dt * 16) = ow;
	v_mfma_f32_16x16x32_bf16 v[28:31], v[220:223], v[2:5], v[28:31]
	s_nop 7
	v_mul_f32_e32 v28, v26, v28
	v_mul_f32_e32 v29, v26, v29
	v_cvt_pk_bf16_f32 v28, v28, v29
	v_mul_f32_e32 v29, v26, v30
	v_mul_f32_e32 v30, v26, v31
	v_cvt_pk_bf16_f32 v29, v29, v30
	v_mov_b32_e32 v248, v28
	v_mov_b32_e32 v249, v29
	ds_read2_b64 v[204:207], v36 offset0:32 offset1:36
	ds_read2_b64 v[208:211], v36 offset0:40 offset1:44
	ds_read2_b64 v[212:215], v36 offset0:48 offset1:52
	ds_read2_b64 v[216:219], v36 offset0:56 offset1:60
	ds_read2_b64 v[220:223], v36 offset0:64 offset1:68
	s_nop 0
	s_waitcnt lgkmcnt(4)
	v_mfma_f32_16x16x32_bf16 v[28:31], v[204:207], v[18:21], 0
	s_waitcnt lgkmcnt(3)
	v_mfma_f32_16x16x32_bf16 v[28:31], v[208:211], v[14:17], v[28:31]
	s_nop 0
	s_waitcnt lgkmcnt(2)
	v_mfma_f32_16x16x32_bf16 v[28:31], v[212:215], v[10:13], v[28:31]
	s_nop 0
	s_waitcnt lgkmcnt(1)
	v_mfma_f32_16x16x32_bf16 v[28:31], v[216:219], v[6:9], v[28:31]
	s_nop 0
	v_add_u32_e32 v36, 0x4000, v27
	s_waitcnt lgkmcnt(0)
	v_mfma_f32_16x16x32_bf16 v[28:31], v[220:223], v[2:5], v[28:31]
	s_nop 7
	v_mul_f32_e32 v28, v26, v28
	v_mul_f32_e32 v29, v26, v29
	v_cvt_pk_bf16_f32 v28, v28, v29
	v_mul_f32_e32 v29, v26, v30
	v_mul_f32_e32 v30, v26, v31
	v_cvt_pk_bf16_f32 v29, v29, v30
	v_mov_b32_e32 v30, v28
	v_mov_b32_e32 v31, v29
	v_mov_b32_e32 v28, v248
	v_mov_b32_e32 v29, v249
	s_nop 1
	v_permlane16_swap_b32_e32 v28, v30
	v_permlane16_swap_b32_e32 v29, v31
	global_store_dwordx4 v[192:193], v[28:31], off
	ds_read2_b64 v[204:207], v36 offset0:64 offset1:68
	ds_read2_b64 v[208:211], v36 offset0:72 offset1:76
	ds_read2_b64 v[212:215], v36 offset0:80 offset1:84
	ds_read2_b64 v[216:219], v36 offset0:88 offset1:92
	ds_read2_b64 v[220:223], v36 offset0:96 offset1:100
	s_nop 0
	s_waitcnt lgkmcnt(4)
	v_mfma_f32_16x16x32_bf16 v[28:31], v[204:207], v[18:21], 0
	s_waitcnt lgkmcnt(3)
	v_mfma_f32_16x16x32_bf16 v[28:31], v[208:211], v[14:17], v[28:31]
	s_nop 0
	s_waitcnt lgkmcnt(2)
	v_mfma_f32_16x16x32_bf16 v[28:31], v[212:215], v[10:13], v[28:31]
	s_nop 0
	s_waitcnt lgkmcnt(1)
	v_mfma_f32_16x16x32_bf16 v[28:31], v[216:219], v[6:9], v[28:31]
	s_nop 0
	v_add_u32_e32 v36, 0x6000, v27
	s_waitcnt lgkmcnt(0)
	v_mfma_f32_16x16x32_bf16 v[28:31], v[220:223], v[2:5], v[28:31]
	s_nop 7
	v_mul_f32_e32 v28, v26, v28
	v_mul_f32_e32 v29, v26, v29
	v_cvt_pk_bf16_f32 v28, v28, v29
	v_mul_f32_e32 v29, v26, v30
	v_mul_f32_e32 v30, v26, v31
	v_cvt_pk_bf16_f32 v29, v29, v30
	v_mov_b32_e32 v248, v28
	v_mov_b32_e32 v249, v29
	ds_read2_b64 v[204:207], v36 offset0:96 offset1:100
	ds_read2_b64 v[208:211], v36 offset0:104 offset1:108
	ds_read2_b64 v[212:215], v36 offset0:112 offset1:116
	ds_read2_b64 v[216:219], v36 offset0:120 offset1:124
	ds_read2_b64 v[220:223], v36 offset0:128 offset1:132
	s_nop 0
	s_waitcnt lgkmcnt(4)
	v_mfma_f32_16x16x32_bf16 v[28:31], v[204:207], v[18:21], 0
	s_waitcnt lgkmcnt(3)
	v_mfma_f32_16x16x32_bf16 v[28:31], v[208:211], v[14:17], v[28:31]
	s_nop 0
	s_waitcnt lgkmcnt(2)
	v_mfma_f32_16x16x32_bf16 v[28:31], v[212:215], v[10:13], v[28:31]
	s_nop 0
	s_waitcnt lgkmcnt(1)
	v_mfma_f32_16x16x32_bf16 v[28:31], v[216:219], v[6:9], v[28:31]
	s_nop 0
	v_add_u32_e32 v36, 0x8000, v27
	s_waitcnt lgkmcnt(0)
	v_mfma_f32_16x16x32_bf16 v[28:31], v[220:223], v[2:5], v[28:31]
	s_nop 7
	v_mul_f32_e32 v28, v26, v28
	v_mul_f32_e32 v29, v26, v29
	v_cvt_pk_bf16_f32 v28, v28, v29
	v_mul_f32_e32 v29, v26, v30
	v_mul_f32_e32 v30, v26, v31
	v_cvt_pk_bf16_f32 v29, v29, v30
	v_mov_b32_e32 v30, v28
	v_mov_b32_e32 v31, v29
	v_mov_b32_e32 v28, v248
	v_mov_b32_e32 v29, v249
	s_nop 1
	v_permlane16_swap_b32_e32 v28, v30
	v_permlane16_swap_b32_e32 v29, v31
	global_store_dwordx4 v[192:193], v[28:31], off offset:64
	ds_read2_b64 v[204:207], v36 offset0:128 offset1:132
	ds_read2_b64 v[208:211], v36 offset0:136 offset1:140
	ds_read2_b64 v[212:215], v36 offset0:144 offset1:148
	ds_read2_b64 v[216:219], v36 offset0:152 offset1:156
	ds_read2_b64 v[220:223], v36 offset0:160 offset1:164
	s_nop 0
	s_waitcnt lgkmcnt(4)
	v_mfma_f32_16x16x32_bf16 v[28:31], v[204:207], v[18:21], 0
	s_waitcnt lgkmcnt(3)
	v_mfma_f32_16x16x32_bf16 v[28:31], v[208:211], v[14:17], v[28:31]
	s_nop 0
	s_waitcnt lgkmcnt(2)
	v_mfma_f32_16x16x32_bf16 v[28:31], v[212:215], v[10:13], v[28:31]
	s_nop 0
	s_waitcnt lgkmcnt(1)
; #define LAS __attribute__((address_space(3)))
; __device__ __forceinline__ unsigned cvt_pk_bf16(float lo, float hi) { unsigned r; asm volatile("v_cvt_pk_bf16_f32 %0, %1, %2" : "=v"(r) : "v"(lo), "v"(hi)); return r; }
; __device__ __forceinline__ void attn_item(const Params& P, int half, int item, LAS unsigned char* lds, unsigned* ctr) {
;     ...
;     for (int dt = 0; dt < 8; ++dt) {
;         f32x4 O = (f32x4){0.f, 0.f, 0.f, 0.f};
;         const LAS unsigned char* vr = Vt + (dt * 16 + c) * VSTR + (m0 + 4 * g) * 2;
; #pragma unroll
;         for (int k5 = 0; k5 < 5; ++k5) { const u32x2 lo = *(const LAS u32x2*)(vr + k5 * 64), hi = *(const LAS u32x2*)(vr + k5 * 64 + 32);
;             const bf16x8 a = as_bf16x8((u32x4){lo.x, lo.y, hi.x, hi.y}); O = __builtin_amdgcn_mfma_f32_16x16x32_bf16(a, Pf[k5], O, 0, 0, 0); }
;         u32x2 ow; ow.x = cvt_pk_bf16(O[0] * inv, O[1] * inv); ow.y = cvt_pk_bf16(O[2] * inv, O[3] * inv);
;         *(u32x2*)(op + dt * 16) = ow;
;     }
;     if (g == 0) LSE[(size_t)qrow * 12 + gi * 4 + hh] = (mx + __builtin_amdgcn_logf(den)) * 0.6931471805599453f;
	v_mfma_f32_16x16x32_bf16 v[28:31], v[216:219], v[6:9], v[28:31]
	s_nop 0
	v_add_u32_e32 v36, 0xa000, v27
	s_waitcnt lgkmcnt(0)
	v_mfma_f32_16x16x32_bf16 v[28:31], v[220:223], v[2:5], v[28:31]
	s_nop 7
	v_mul_f32_e32 v28, v26, v28
	v_mul_f32_e32 v29, v26, v29
	v_cvt_pk_bf16_f32 v28, v28, v29
	v_mul_f32_e32 v29, v26, v30
	v_mul_f32_e32 v30, v26, v31
	v_cvt_pk_bf16_f32 v29, v29, v30
	v_mov_b32_e32 v248, v28
	v_mov_b32_e32 v249, v29
	ds_read2_b64 v[204:207], v36 offset0:160 offset1:164
	ds_read2_b64 v[208:211], v36 offset0:168 offset1:172
	ds_read2_b64 v[212:215], v36 offset0:176 offset1:180
	ds_read2_b64 v[216:219], v36 offset0:184 offset1:188
	ds_read2_b64 v[220:223], v36 offset0:192 offset1:196
	s_nop 0
	s_waitcnt lgkmcnt(4)
	v_mfma_f32_16x16x32_bf16 v[28:31], v[204:207], v[18:21], 0
	s_waitcnt lgkmcnt(3)
	v_mfma_f32_16x16x32_bf16 v[28:31], v[208:211], v[14:17], v[28:31]
	s_nop 0
	s_waitcnt lgkmcnt(2)
	v_mfma_f32_16x16x32_bf16 v[28:31], v[212:215], v[10:13], v[28:31]
	s_nop 0
	s_waitcnt lgkmcnt(1)
	v_mfma_f32_16x16x32_bf16 v[28:31], v[216:219], v[6:9], v[28:31]
	s_nop 0
	v_add_u32_e32 v36, 0xc000, v27
	s_waitcnt lgkmcnt(0)
	v_mfma_f32_16x16x32_bf16 v[28:31], v[220:223], v[2:5], v[28:31]
	s_nop 7
	v_mul_f32_e32 v28, v26, v28
	v_mul_f32_e32 v29, v26, v29
	v_cvt_pk_bf16_f32 v28, v28, v29
	v_mul_f32_e32 v29, v26, v30
	v_mul_f32_e32 v30, v26, v31
	v_cvt_pk_bf16_f32 v29, v29, v30
	v_mov_b32_e32 v30, v28
	v_mov_b32_e32 v31, v29
	v_mov_b32_e32 v28, v248
	v_mov_b32_e32 v29, v249
	s_nop 1
	v_permlane16_swap_b32_e32 v28, v30
	v_permlane16_swap_b32_e32 v29, v31
	global_store_dwordx4 v[192:193], v[28:31], off offset:128
	ds_read2_b64 v[204:207], v36 offset0:192 offset1:196
	ds_read2_b64 v[208:211], v36 offset0:200 offset1:204
	ds_read2_b64 v[212:215], v36 offset0:208 offset1:212
	ds_read2_b64 v[216:219], v36 offset0:216 offset1:220
	ds_read2_b64 v[220:223], v36 offset0:224 offset1:228
	s_nop 0
	s_waitcnt lgkmcnt(4)
	v_mfma_f32_16x16x32_bf16 v[28:31], v[204:207], v[18:21], 0
	s_waitcnt lgkmcnt(3)
	v_mfma_f32_16x16x32_bf16 v[28:31], v[208:211], v[14:17], v[28:31]
	s_nop 0
	s_waitcnt lgkmcnt(2)
	v_mfma_f32_16x16x32_bf16 v[28:31], v[212:215], v[10:13], v[28:31]
	s_nop 0
	s_waitcnt lgkmcnt(1)
	v_mfma_f32_16x16x32_bf16 v[28:31], v[216:219], v[6:9], v[28:31]
	s_nop 0
	s_waitcnt lgkmcnt(0)
	v_mfma_f32_16x16x32_bf16 v[28:31], v[220:223], v[2:5], v[28:31]
	v_add_u32_e32 v32, 0xe000, v27
	s_nop 6
	v_mul_f32_e32 v28, v26, v28
	v_mul_f32_e32 v29, v26, v29
	v_cvt_pk_bf16_f32 v28, v28, v29
	v_mul_f32_e32 v29, v26, v30
	v_mul_f32_e32 v30, v26, v31
	v_cvt_pk_bf16_f32 v29, v29, v30
	v_mov_b32_e32 v248, v28
	v_mov_b32_e32 v249, v29
	ds_read2_b64 v[28:31], v32 offset0:224 offset1:228
	s_waitcnt lgkmcnt(0)
	v_mfma_f32_16x16x32_bf16 v[18:21], v[28:31], v[18:21], 0
	ds_read2_b64 v[28:31], v32 offset0:232 offset1:236
	s_waitcnt lgkmcnt(0)
	v_mfma_f32_16x16x32_bf16 v[14:17], v[28:31], v[14:17], v[18:21]
	s_nop 4
	ds_read2_b64 v[18:21], v32 offset0:240 offset1:244
	s_waitcnt lgkmcnt(0)
	v_mfma_f32_16x16x32_bf16 v[10:13], v[18:21], v[10:13], v[14:17]
	s_nop 2
	ds_read2_b64 v[14:17], v32 offset0:248 offset1:252
	s_waitcnt lgkmcnt(0)
	v_mfma_f32_16x16x32_bf16 v[6:9], v[14:17], v[6:9], v[10:13]
	s_nop 2
	v_add_u32_e32 v10, 0xe800, v27
	ds_read2_b64 v[10:13], v10 offset1:4
	s_waitcnt lgkmcnt(0)
	v_mfma_f32_16x16x32_bf16 v[2:5], v[10:13], v[2:5], v[6:9]
	s_nop 7
	v_mul_f32_e32 v2, v26, v2
	v_mul_f32_e32 v3, v26, v3
	v_cvt_pk_bf16_f32 v2, v2, v3
	v_mul_f32_e32 v3, v26, v4
	v_mul_f32_e32 v4, v26, v5
	v_cvt_pk_bf16_f32 v3, v3, v4
	v_mov_b32_e32 v30, v2
	v_mov_b32_e32 v31, v3
	v_mov_b32_e32 v28, v248
	v_mov_b32_e32 v29, v249
	s_nop 1
	v_permlane16_swap_b32_e32 v28, v30
	v_permlane16_swap_b32_e32 v29, v31
	global_store_dwordx4 v[192:193], v[28:31], off offset:192
	s_and_saveexec_b64 s[30:31], vcc
	s_cbranch_execz .LBB0_541
	v_log_f32_e32 v2, v25
	v_readlane_b32 s8, v251, 33
	s_lshl_b32 s6, s2, 2
	v_readlane_b32 s9, v251, 34
	v_add_f32_e32 v2, v24, v2
	s_ashr_i32 s7, s6, 31
	v_mul_f32_e32 v4, 0x3f317218, v2
	v_mad_i64_i32 v[2:3], s[8:9], v133, 48, s[8:9]
	v_lshl_add_u64 v[2:3], s[6:7], 2, v[2:3]
	s_lshl_b32 s20, s4, 2
	v_lshl_add_u64 v[2:3], v[2:3], 0, s[20:21]
	global_store_dword v[2:3], v4, off
